# v27 plus grid-barrier waiters polling the global generation word directly (one polling hop instead of two)
# speedup vs baseline: 1.0034x; 1.0034x over previous
.LBB0_151:
	s_or_b64 exec, exec, s[4:5]
	v_cvt_f32_u32_e32 v5, v3
	s_waitcnt vmcnt(0)
	v_readfirstlane_b32 s2, v4
	v_sub_u32_e32 v4, 0, v3
	v_rcp_iflag_f32_e32 v5, v5
	v_add_u32_e32 v6, s2, v0
	v_mul_f32_e32 v5, 0x4f7ffffe, v5
	v_cvt_u32_f32_e32 v5, v5
	v_mul_lo_u32 v0, v4, v5
	v_mul_hi_u32 v0, v5, v0
	v_add_u32_e32 v0, v5, v0
	v_mul_hi_u32 v0, v6, v0
	v_mul_lo_u32 v4, v0, v3
	v_sub_u32_e32 v4, v6, v4
	v_add_u32_e32 v5, 1, v0
	v_cmp_ge_u32_e32 vcc, v4, v3
	s_nop 1
	v_cndmask_b32_e32 v0, v0, v5, vcc
	v_sub_u32_e32 v5, v4, v3
	v_cndmask_b32_e32 v4, v4, v5, vcc
	v_add_u32_e32 v5, 1, v0
	v_cmp_ge_u32_e32 vcc, v4, v3
	v_add_u32_e32 v4, 1, v6
	s_nop 0
	v_cndmask_b32_e32 v0, v0, v5, vcc
	v_mul_lo_u32 v5, v3, v0
	v_add_u32_e32 v3, v5, v3
	v_cmp_ne_u32_e32 vcc, v4, v3
	s_and_saveexec_b64 s[4:5], vcc
	s_xor_b64 s[4:5], exec, s[4:5]
	s_cbranch_execz .LBB0_165
	v_readlane_b32 s6, v252, 20
	v_readlane_b32 s7, v252, 21
	s_waitcnt lgkmcnt(0)
	s_nop 3
	global_load_dword v2, v1, s[6:7] sc1
	s_waitcnt vmcnt(0)
	v_cmp_eq_u32_e32 vcc, v2, v0
	s_and_saveexec_b64 s[6:7], vcc
	s_cbranch_execz .LBB0_164
	s_mov_b32 s2, 1
	s_mov_b64 s[8:9], 0
	s_branch .LBB0_155
